# hand-written neighbourhood-attention tiles: all K/bias loads of a tile issued up front, V loads follow as registers free up
# speedup vs baseline: 1.1338x; 1.0067x over previous
.LBB0_1072:
	s_cmp_gt_i32 s66, 1
	s_mov_b64 s[0:1], -1
	s_cbranch_scc0 .LBB0_1115
	s_mov_b64 exec, -1
	v_writelane_b32 v245, s0, 0
	v_writelane_b32 v245, s1, 1
	v_writelane_b32 v245, s2, 2
	v_writelane_b32 v245, s3, 3
	v_writelane_b32 v245, s4, 4
	v_writelane_b32 v245, s5, 5
	v_writelane_b32 v245, s6, 6
	v_writelane_b32 v245, s7, 7
	v_writelane_b32 v245, s8, 8
	v_writelane_b32 v245, s9, 9
	v_writelane_b32 v245, s10, 10
	v_writelane_b32 v245, s11, 11
	v_writelane_b32 v245, s12, 12
	v_writelane_b32 v245, s13, 13
	v_writelane_b32 v245, s14, 14
	v_writelane_b32 v245, s15, 15
	v_writelane_b32 v245, s16, 16
	v_writelane_b32 v245, s17, 17
	v_writelane_b32 v245, s18, 18
	v_writelane_b32 v245, s19, 19
	v_writelane_b32 v245, s20, 20
	v_writelane_b32 v245, s21, 21
	v_writelane_b32 v245, s22, 22
	v_writelane_b32 v245, s23, 23
	v_writelane_b32 v245, s24, 24
	v_writelane_b32 v245, s25, 25
	v_writelane_b32 v245, s26, 26
	v_writelane_b32 v245, s27, 27
	v_writelane_b32 v245, s28, 28
	v_writelane_b32 v245, s29, 29
	v_writelane_b32 v245, s30, 30
	v_writelane_b32 v245, s31, 31
	v_writelane_b32 v245, s32, 32
	v_writelane_b32 v245, s33, 33
	v_writelane_b32 v245, s34, 34
	v_writelane_b32 v245, s35, 35
	v_writelane_b32 v245, s36, 36
	v_writelane_b32 v245, s37, 37
	v_writelane_b32 v245, s38, 38
	v_writelane_b32 v245, s39, 39
	v_writelane_b32 v245, s40, 40
	v_writelane_b32 v245, s41, 41
	v_writelane_b32 v245, s42, 42
	v_writelane_b32 v245, s43, 43
	v_writelane_b32 v245, s44, 44
	v_writelane_b32 v245, s45, 45
	v_writelane_b32 v245, s46, 46
	v_writelane_b32 v245, s47, 47
	v_writelane_b32 v245, s48, 48
	v_writelane_b32 v245, s49, 49
	v_writelane_b32 v245, s50, 50
	v_writelane_b32 v245, s51, 51
	v_writelane_b32 v245, s52, 52
	v_writelane_b32 v245, s53, 53
	v_writelane_b32 v245, s54, 54
	v_writelane_b32 v245, s55, 55
	v_writelane_b32 v245, s56, 56
	v_writelane_b32 v245, s57, 57
	v_writelane_b32 v245, s58, 58
	v_writelane_b32 v245, s59, 59
	v_writelane_b32 v245, s60, 60
	v_writelane_b32 v245, s61, 61
	v_writelane_b32 v245, s62, 62
	v_writelane_b32 v245, s63, 63
	v_writelane_b32 v244, s64, 0
	v_writelane_b32 v244, s65, 1
	v_writelane_b32 v244, s66, 2
	v_writelane_b32 v244, s67, 3
	v_writelane_b32 v244, s68, 4
	v_writelane_b32 v244, s69, 5
	v_writelane_b32 v244, s70, 6
	v_writelane_b32 v244, s71, 7
	v_writelane_b32 v244, s72, 8
	v_writelane_b32 v244, s73, 9
	v_writelane_b32 v244, s74, 10
	v_writelane_b32 v244, s75, 11
	v_writelane_b32 v244, s76, 12
	v_writelane_b32 v244, s77, 13
	v_writelane_b32 v244, s78, 14
	v_writelane_b32 v244, s79, 15
	v_lshrrev_b32_e32 v235, 6, v225
	v_and_b32_e32 v246, 63, v225
	s_load_dwordx2 s[10:11], s[100:101], 0xb0
	s_load_dwordx2 s[12:13], s[100:101], 0x28
	v_readfirstlane_b32 s4, v235
	v_and_b32_e32 v236, 15, v246
	v_lshrrev_b32_e32 v237, 4, v246
	s_nop 3
	s_and_b32 s5, s4, 3
	s_lshr_b32 s6, s4, 2
	s_lshl_b32 s7, s99, 1
	s_add_u32 s7, s7, s6
	s_lshl_b32 s8, s5, 4
	s_sub_i32 s8, s8, 8
	s_max_i32 s8, s8, 0
	s_min_i32 s8, s8, 32
	s_lshl_b32 s9, s5, 4
	v_lshrrev_b32_e32 v240, 2, v236
	v_and_b32_e32 v241, 3, v236
	v_lshl_add_u32 v240, v240, 3, v241
	v_lshlrev_b32_e32 v240, 10, v240
	v_lshl_add_u32 v218, v237, 4, v240
	v_add_u32_e32 v219, 0x1000, v218
	v_lshlrev_b32_e32 v240, 12, v236
	v_lshl_add_u32 v220, v237, 4, v240
	v_lshlrev_b32_e32 v240, 10, v236
	v_lshl_add_u32 v221, v237, 4, v240
	v_mul_u32_u24_e32 v240, 0xc00, v236
	v_lshl_add_u32 v222, v237, 3, v240
	v_xor_b32_e32 v223, 16, v246
	v_lshlrev_b32_e32 v223, 2, v223
	v_xor_b32_e32 v232, 32, v246
	v_lshlrev_b32_e32 v232, 2, v232
	v_add_u32_e32 v240, s9, v236
	v_lshl_add_u32 v241, v237, 3, s8
	v_sub_u32_e32 v235, v241, v240
	v_subrev_u32_e32 v240, 8, v240
	v_med3_i32 v240, v240, 0, 48
	v_sub_u32_e32 v241, v241, v240
	v_add_u32_e32 v240, 0, v235
	v_med3_i32 v240, v240, -15, 15
	v_add_u32_e32 v240, 15, v240
	v_lshlrev_b32_e32 v210, 2, v240
	v_add_u32_e32 v240, 0, v241
	v_cmp_gt_u32_e64 s[40:41], 16, v240
	v_add_u32_e32 v240, 1, v235
	v_med3_i32 v240, v240, -15, 15
	v_add_u32_e32 v240, 15, v240
	v_lshlrev_b32_e32 v211, 2, v240
	v_add_u32_e32 v240, 1, v241
	v_cmp_gt_u32_e64 s[42:43], 16, v240
	v_add_u32_e32 v240, 2, v235
	v_med3_i32 v240, v240, -15, 15
	v_add_u32_e32 v240, 15, v240
	v_lshlrev_b32_e32 v212, 2, v240
	v_add_u32_e32 v240, 2, v241
	v_cmp_gt_u32_e64 s[44:45], 16, v240
	v_add_u32_e32 v240, 3, v235
	v_med3_i32 v240, v240, -15, 15
	v_add_u32_e32 v240, 15, v240
	v_lshlrev_b32_e32 v213, 2, v240
	v_add_u32_e32 v240, 3, v241
	v_cmp_gt_u32_e64 s[46:47], 16, v240
	v_add_u32_e32 v240, 4, v235
	v_med3_i32 v240, v240, -15, 15
	v_add_u32_e32 v240, 15, v240
	v_lshlrev_b32_e32 v214, 2, v240
	v_add_u32_e32 v240, 4, v241
	v_cmp_gt_u32_e64 s[48:49], 16, v240
	v_add_u32_e32 v240, 5, v235
	v_med3_i32 v240, v240, -15, 15
	v_add_u32_e32 v240, 15, v240
	v_lshlrev_b32_e32 v215, 2, v240
	v_add_u32_e32 v240, 5, v241
	v_cmp_gt_u32_e64 s[50:51], 16, v240
	v_add_u32_e32 v240, 6, v235
	v_med3_i32 v240, v240, -15, 15
	v_add_u32_e32 v240, 15, v240
	v_lshlrev_b32_e32 v216, 2, v240
	v_add_u32_e32 v240, 6, v241
	v_cmp_gt_u32_e64 s[52:53], 16, v240
	v_add_u32_e32 v240, 7, v235
	v_med3_i32 v240, v240, -15, 15
	v_add_u32_e32 v240, 15, v240
	v_lshlrev_b32_e32 v217, 2, v240
	v_add_u32_e32 v240, 7, v241
	v_cmp_gt_u32_e64 s[54:55], 16, v240
	s_waitcnt lgkmcnt(0)
	s_mov_b32 s14, 0
.Lna_tile:
	s_and_b32 s15, s7, 7
	s_bfe_u32 s16, s7, 0x50003
	s_lshr_b32 s17, s7, 8
	s_sub_i32 s18, s16, 4
	s_max_i32 s18, s18, 0
	s_min_i32 s18, s18, 24
	s_lshl_b32 s19, s17, 11
	s_lshl_b32 s20, s18, 6
	s_add_u32 s20, s20, s19
	s_add_u32 s20, s20, s8
	s_lshl_b32 s21, s16, 6
	s_add_u32 s21, s21, s19
	s_add_u32 s21, s21, s9
	s_lshl_b32 s22, s15, 7
	s_lshl_b32 s23, s20, 10
	s_add_u32 s23, s23, s22
	s_add_u32 s0, s10, 0x5200000
	s_addc_u32 s1, s11, 0
	s_add_u32 s0, s0, s23
	s_addc_u32 s1, s1, 0
	s_lshl_b32 s23, s17, 3
	s_add_u32 s23, s23, s15
	s_lshl_b32 s23, s23, 18
	s_sub_u32 s24, s20, s19
	s_lshl_b32 s24, s24, 1
	s_add_u32 s23, s23, s24
	s_add_u32 s24, s10, 0x6200000
	s_addc_u32 s25, s11, 0
	s_add_u32 s24, s24, s23
	s_addc_u32 s25, s25, 0
	s_add_u32 s26, s24, 0x10000
	s_addc_u32 s27, s25, 0
	s_add_u32 s28, s26, 0x10000
	s_addc_u32 s29, s27, 0
	s_add_u32 s30, s28, 0x10000
	s_addc_u32 s31, s29, 0
	s_lshl_b32 s23, s21, 10
	s_add_u32 s23, s23, s22
	s_add_u32 s2, s10, 0x4200000
	s_addc_u32 s3, s11, 0
	s_add_u32 s2, s2, s23
	s_addc_u32 s3, s3, 0
	s_mul_i32 s23, s21, 0xc00
	s_add_u32 s23, s23, s22
	s_add_u32 s32, s10, 0xc200000
	s_addc_u32 s33, s11, 0
	s_add_u32 s32, s32, s23
	s_addc_u32 s33, s33, 0
	s_mul_i32 s23, s15, 465
	s_sub_i32 s34, s18, s16
	s_add_i32 s34, s34, 7
	s_mul_i32 s34, s34, 31
	s_add_u32 s23, s23, s34
	s_lshl_b32 s23, s23, 2
	s_add_u32 s34, s12, s23
	s_addc_u32 s35, s13, 0
	global_load_dwordx4 v[0:3], v221, s[2:3]
	global_load_dwordx4 v[4:7], v221, s[2:3] offset:64
	global_load_dwordx4 v[72:75], v218, s[0:1]
	global_load_dwordx4 v[76:79], v218, s[0:1] offset:64
	global_load_dwordx4 v[80:83], v219, s[0:1]
	global_load_dwordx4 v[84:87], v219, s[0:1] offset:64
	s_add_u32 s0, s0, 0x10000
	s_addc_u32 s1, s1, 0
	global_load_dword v8, v210, s[34:35]
	global_load_dword v9, v211, s[34:35]
	global_load_dword v10, v212, s[34:35]
	global_load_dword v11, v213, s[34:35]
	global_load_dword v12, v214, s[34:35]
	global_load_dword v13, v215, s[34:35]
	global_load_dword v14, v216, s[34:35]
	global_load_dword v15, v217, s[34:35]
	global_load_dwordx4 v[88:91], v218, s[0:1]
	global_load_dwordx4 v[92:95], v218, s[0:1] offset:64
	global_load_dwordx4 v[96:99], v219, s[0:1]
	global_load_dwordx4 v[100:103], v219, s[0:1] offset:64
	s_add_u32 s0, s0, 0x10000
	s_addc_u32 s1, s1, 0
	global_load_dword v16, v210, s[34:35] offset:124
	global_load_dword v17, v211, s[34:35] offset:124
	global_load_dword v18, v212, s[34:35] offset:124
	global_load_dword v19, v213, s[34:35] offset:124
	global_load_dword v20, v214, s[34:35] offset:124
	global_load_dword v21, v215, s[34:35] offset:124
	global_load_dword v22, v216, s[34:35] offset:124
	global_load_dword v23, v217, s[34:35] offset:124
	global_load_dwordx4 v[104:107], v218, s[0:1]
	global_load_dwordx4 v[108:111], v218, s[0:1] offset:64
	global_load_dwordx4 v[112:115], v219, s[0:1]
	global_load_dwordx4 v[116:119], v219, s[0:1] offset:64
	s_add_u32 s0, s0, 0x10000
	s_addc_u32 s1, s1, 0
	global_load_dword v24, v210, s[34:35] offset:248
	global_load_dword v25, v211, s[34:35] offset:248
	global_load_dword v26, v212, s[34:35] offset:248
	global_load_dword v27, v213, s[34:35] offset:248
	global_load_dword v28, v214, s[34:35] offset:248
	global_load_dword v29, v215, s[34:35] offset:248
	global_load_dword v30, v216, s[34:35] offset:248
	global_load_dword v31, v217, s[34:35] offset:248
	global_load_dwordx4 v[120:123], v218, s[0:1]
	global_load_dwordx4 v[124:127], v218, s[0:1] offset:64
	global_load_dwordx4 v[128:131], v219, s[0:1]
	global_load_dwordx4 v[132:135], v219, s[0:1] offset:64
	s_add_u32 s0, s0, 0x10000
	s_addc_u32 s1, s1, 0
	global_load_dword v32, v210, s[34:35] offset:372
	global_load_dword v33, v211, s[34:35] offset:372
	global_load_dword v34, v212, s[34:35] offset:372
	global_load_dword v35, v213, s[34:35] offset:372
	global_load_dword v36, v214, s[34:35] offset:372
	global_load_dword v37, v215, s[34:35] offset:372
	global_load_dword v38, v216, s[34:35] offset:372
	global_load_dword v39, v217, s[34:35] offset:372
	global_load_dwordx4 v[146:149], v218, s[0:1]
	global_load_dwordx4 v[150:153], v218, s[0:1] offset:64
	global_load_dwordx4 v[154:157], v219, s[0:1]
	global_load_dwordx4 v[158:161], v219, s[0:1] offset:64
	s_add_u32 s0, s0, 0x10000
	s_addc_u32 s1, s1, 0
	global_load_dword v40, v210, s[34:35] offset:496
	global_load_dword v41, v211, s[34:35] offset:496
	global_load_dword v42, v212, s[34:35] offset:496
	global_load_dword v43, v213, s[34:35] offset:496
	global_load_dword v44, v214, s[34:35] offset:496
	global_load_dword v45, v215, s[34:35] offset:496
	global_load_dword v46, v216, s[34:35] offset:496
	global_load_dword v47, v217, s[34:35] offset:496
	global_load_dwordx4 v[162:165], v218, s[0:1]
	global_load_dwordx4 v[166:169], v218, s[0:1] offset:64
	global_load_dwordx4 v[170:173], v219, s[0:1]
	global_load_dwordx4 v[174:177], v219, s[0:1] offset:64
	s_add_u32 s0, s0, 0x10000
	s_addc_u32 s1, s1, 0
	global_load_dword v48, v210, s[34:35] offset:620
	global_load_dword v49, v211, s[34:35] offset:620
	global_load_dword v50, v212, s[34:35] offset:620
	global_load_dword v51, v213, s[34:35] offset:620
	global_load_dword v52, v214, s[34:35] offset:620
	global_load_dword v53, v215, s[34:35] offset:620
	global_load_dword v54, v216, s[34:35] offset:620
	global_load_dword v55, v217, s[34:35] offset:620
	global_load_dword v56, v210, s[34:35] offset:744
	global_load_dword v57, v211, s[34:35] offset:744
	global_load_dword v58, v212, s[34:35] offset:744
	global_load_dword v59, v213, s[34:35] offset:744
	global_load_dword v60, v214, s[34:35] offset:744
	global_load_dword v61, v215, s[34:35] offset:744
	global_load_dword v62, v216, s[34:35] offset:744
	global_load_dword v63, v217, s[34:35] offset:744
	global_load_dword v64, v210, s[34:35] offset:868
	global_load_dword v65, v211, s[34:35] offset:868
	global_load_dword v66, v212, s[34:35] offset:868
	global_load_dword v67, v213, s[34:35] offset:868
	global_load_dword v68, v214, s[34:35] offset:868
	global_load_dword v69, v215, s[34:35] offset:868
	global_load_dword v70, v216, s[34:35] offset:868
	global_load_dword v71, v217, s[34:35] offset:868
	v_mov_b32_e32 v178, 0
	v_mov_b32_e32 v179, 0
	v_mov_b32_e32 v180, 0
	v_mov_b32_e32 v181, 0
	v_mov_b32_e32 v182, 0
	v_mov_b32_e32 v183, 0
	v_mov_b32_e32 v184, 0
	v_mov_b32_e32 v185, 0
	v_mov_b32_e32 v186, 0
	v_mov_b32_e32 v187, 0
	v_mov_b32_e32 v188, 0
	v_mov_b32_e32 v189, 0
	v_mov_b32_e32 v190, 0
	v_mov_b32_e32 v191, 0
	v_mov_b32_e32 v192, 0
	v_mov_b32_e32 v193, 0
	s_waitcnt vmcnt(63)
	v_mfma_f32_16x16x32_bf16 v[194:197], v[72:75], v[0:3], 0
	v_mfma_f32_16x16x32_bf16 v[198:201], v[80:83], v[0:3], 0
	v_mfma_f32_16x16x32_bf16 v[194:197], v[76:79], v[4:7], v[194:197]
	v_mfma_f32_16x16x32_bf16 v[198:201], v[84:87], v[4:7], v[198:201]
	global_load_dwordx4 v[72:75], v218, s[0:1]
	global_load_dwordx4 v[76:79], v218, s[0:1] offset:64
	global_load_dwordx4 v[80:83], v219, s[0:1]
	global_load_dwordx4 v[84:87], v219, s[0:1] offset:64
	s_add_u32 s0, s0, 0x10000
	s_addc_u32 s1, s1, 0
	s_waitcnt vmcnt(63)
	v_mfma_f32_16x16x32_bf16 v[202:205], v[88:91], v[0:3], 0
	v_mfma_f32_16x16x32_bf16 v[206:209], v[96:99], v[0:3], 0
	v_mfma_f32_16x16x32_bf16 v[202:205], v[92:95], v[4:7], v[202:205]
	v_mfma_f32_16x16x32_bf16 v[206:209], v[100:103], v[4:7], v[206:209]
	global_load_dwordx4 v[88:91], v218, s[0:1]
	global_load_dwordx4 v[92:95], v218, s[0:1] offset:64
	global_load_dwordx4 v[96:99], v219, s[0:1]
	global_load_dwordx4 v[100:103], v219, s[0:1] offset:64
	s_add_u32 s0, s0, 0x10000
	s_addc_u32 s1, s1, 0
	s_waitcnt vmcnt(63)
	v_fmamk_f32 v235, v8, 0x3fb8aa3b, v194
	v_mov_b32_e32 v8, 0xff800000
	v_cndmask_b32_e64 v8, v8, v235, s[40:41]
	v_fmamk_f32 v235, v9, 0x3fb8aa3b, v195
	v_mov_b32_e32 v9, 0xff800000
	v_cndmask_b32_e64 v9, v9, v235, s[42:43]
	v_fmamk_f32 v235, v10, 0x3fb8aa3b, v196
	v_mov_b32_e32 v10, 0xff800000
	v_cndmask_b32_e64 v10, v10, v235, s[44:45]
	v_fmamk_f32 v235, v11, 0x3fb8aa3b, v197
	v_mov_b32_e32 v11, 0xff800000
	v_cndmask_b32_e64 v11, v11, v235, s[46:47]
	v_fmamk_f32 v235, v12, 0x3fb8aa3b, v198
	v_mov_b32_e32 v12, 0xff800000
	v_cndmask_b32_e64 v12, v12, v235, s[48:49]
	v_fmamk_f32 v235, v13, 0x3fb8aa3b, v199
	v_mov_b32_e32 v13, 0xff800000
	v_cndmask_b32_e64 v13, v13, v235, s[50:51]
	v_fmamk_f32 v235, v14, 0x3fb8aa3b, v200
	v_mov_b32_e32 v14, 0xff800000
	v_cndmask_b32_e64 v14, v14, v235, s[52:53]
	v_fmamk_f32 v235, v15, 0x3fb8aa3b, v201
	v_mov_b32_e32 v15, 0xff800000
	v_cndmask_b32_e64 v15, v15, v235, s[54:55]
	s_waitcnt vmcnt(63)
	v_mfma_f32_16x16x32_bf16 v[194:197], v[104:107], v[0:3], 0
	v_mfma_f32_16x16x32_bf16 v[198:201], v[112:115], v[0:3], 0
	v_mfma_f32_16x16x32_bf16 v[194:197], v[108:111], v[4:7], v[194:197]
	v_mfma_f32_16x16x32_bf16 v[198:201], v[116:119], v[4:7], v[198:201]
	global_load_dwordx4 v[104:107], v220, s[24:25]
	global_load_dwordx4 v[108:111], v220, s[26:27]
	global_load_dwordx4 v[112:115], v220, s[28:29]
	global_load_dwordx4 v[116:119], v220, s[30:31]
	s_waitcnt vmcnt(63)
	v_fmamk_f32 v235, v16, 0x3fb8aa3b, v202
	v_mov_b32_e32 v16, 0xff800000
	v_cndmask_b32_e64 v16, v16, v235, s[40:41]
	v_fmamk_f32 v235, v17, 0x3fb8aa3b, v203
	v_mov_b32_e32 v17, 0xff800000
	v_cndmask_b32_e64 v17, v17, v235, s[42:43]
	v_fmamk_f32 v235, v18, 0x3fb8aa3b, v204
	v_mov_b32_e32 v18, 0xff800000
	v_cndmask_b32_e64 v18, v18, v235, s[44:45]
	v_fmamk_f32 v235, v19, 0x3fb8aa3b, v205
	v_mov_b32_e32 v19, 0xff800000
	v_cndmask_b32_e64 v19, v19, v235, s[46:47]
	v_fmamk_f32 v235, v20, 0x3fb8aa3b, v206
	v_mov_b32_e32 v20, 0xff800000
	v_cndmask_b32_e64 v20, v20, v235, s[48:49]
	v_fmamk_f32 v235, v21, 0x3fb8aa3b, v207
	v_mov_b32_e32 v21, 0xff800000
	v_cndmask_b32_e64 v21, v21, v235, s[50:51]
	v_fmamk_f32 v235, v22, 0x3fb8aa3b, v208
	v_mov_b32_e32 v22, 0xff800000
	v_cndmask_b32_e64 v22, v22, v235, s[52:53]
	v_fmamk_f32 v235, v23, 0x3fb8aa3b, v209
	v_mov_b32_e32 v23, 0xff800000
	v_cndmask_b32_e64 v23, v23, v235, s[54:55]
	s_waitcnt vmcnt(60)
	v_mfma_f32_16x16x32_bf16 v[202:205], v[120:123], v[0:3], 0
	v_mfma_f32_16x16x32_bf16 v[206:209], v[128:131], v[0:3], 0
	v_mfma_f32_16x16x32_bf16 v[202:205], v[124:127], v[4:7], v[202:205]
	v_mfma_f32_16x16x32_bf16 v[206:209], v[132:135], v[4:7], v[206:209]
	global_load_dwordx4 v[120:123], v220, s[24:25] offset:128
	global_load_dwordx4 v[124:127], v220, s[26:27] offset:128
	global_load_dwordx4 v[128:131], v220, s[28:29] offset:128
	global_load_dwordx4 v[132:135], v220, s[30:31] offset:128
	s_waitcnt vmcnt(63)
	v_fmamk_f32 v235, v24, 0x3fb8aa3b, v194
	v_mov_b32_e32 v24, 0xff800000
	v_cndmask_b32_e64 v24, v24, v235, s[40:41]
	v_fmamk_f32 v235, v25, 0x3fb8aa3b, v195
	v_mov_b32_e32 v25, 0xff800000
	v_cndmask_b32_e64 v25, v25, v235, s[42:43]
	v_fmamk_f32 v235, v26, 0x3fb8aa3b, v196
	v_mov_b32_e32 v26, 0xff800000
	v_cndmask_b32_e64 v26, v26, v235, s[44:45]
	v_fmamk_f32 v235, v27, 0x3fb8aa3b, v197
	v_mov_b32_e32 v27, 0xff800000
	v_cndmask_b32_e64 v27, v27, v235, s[46:47]
	v_fmamk_f32 v235, v28, 0x3fb8aa3b, v198
	v_mov_b32_e32 v28, 0xff800000
	v_cndmask_b32_e64 v28, v28, v235, s[48:49]
	v_fmamk_f32 v235, v29, 0x3fb8aa3b, v199
	v_mov_b32_e32 v29, 0xff800000
	v_cndmask_b32_e64 v29, v29, v235, s[50:51]
	v_fmamk_f32 v235, v30, 0x3fb8aa3b, v200
	v_mov_b32_e32 v30, 0xff800000
	v_cndmask_b32_e64 v30, v30, v235, s[52:53]
	v_fmamk_f32 v235, v31, 0x3fb8aa3b, v201
	v_mov_b32_e32 v31, 0xff800000
	v_cndmask_b32_e64 v31, v31, v235, s[54:55]
	s_waitcnt vmcnt(52)
	v_mfma_f32_16x16x32_bf16 v[194:197], v[146:149], v[0:3], 0
	v_mfma_f32_16x16x32_bf16 v[198:201], v[154:157], v[0:3], 0
	v_mfma_f32_16x16x32_bf16 v[194:197], v[150:153], v[4:7], v[194:197]
	v_mfma_f32_16x16x32_bf16 v[198:201], v[158:161], v[4:7], v[198:201]
	global_load_dwordx4 v[146:149], v220, s[24:25] offset:256
	global_load_dwordx4 v[150:153], v220, s[26:27] offset:256
	global_load_dwordx4 v[154:157], v220, s[28:29] offset:256
	global_load_dwordx4 v[158:161], v220, s[30:31] offset:256
	s_waitcnt vmcnt(60)
	v_fmamk_f32 v235, v32, 0x3fb8aa3b, v202
	v_mov_b32_e32 v32, 0xff800000
	v_cndmask_b32_e64 v32, v32, v235, s[40:41]
	v_fmamk_f32 v235, v33, 0x3fb8aa3b, v203
	v_mov_b32_e32 v33, 0xff800000
	v_cndmask_b32_e64 v33, v33, v235, s[42:43]
	v_fmamk_f32 v235, v34, 0x3fb8aa3b, v204
	v_mov_b32_e32 v34, 0xff800000
	v_cndmask_b32_e64 v34, v34, v235, s[44:45]
	v_fmamk_f32 v235, v35, 0x3fb8aa3b, v205
	v_mov_b32_e32 v35, 0xff800000
	v_cndmask_b32_e64 v35, v35, v235, s[46:47]
	v_fmamk_f32 v235, v36, 0x3fb8aa3b, v206
	v_mov_b32_e32 v36, 0xff800000
	v_cndmask_b32_e64 v36, v36, v235, s[48:49]
	v_fmamk_f32 v235, v37, 0x3fb8aa3b, v207
	v_mov_b32_e32 v37, 0xff800000
	v_cndmask_b32_e64 v37, v37, v235, s[50:51]
	v_fmamk_f32 v235, v38, 0x3fb8aa3b, v208
	v_mov_b32_e32 v38, 0xff800000
	v_cndmask_b32_e64 v38, v38, v235, s[52:53]
	v_fmamk_f32 v235, v39, 0x3fb8aa3b, v209
	v_mov_b32_e32 v39, 0xff800000
	v_cndmask_b32_e64 v39, v39, v235, s[54:55]
	s_waitcnt vmcnt(44)
	v_mfma_f32_16x16x32_bf16 v[202:205], v[162:165], v[0:3], 0
	v_mfma_f32_16x16x32_bf16 v[206:209], v[170:173], v[0:3], 0
	v_mfma_f32_16x16x32_bf16 v[202:205], v[166:169], v[4:7], v[202:205]
	v_mfma_f32_16x16x32_bf16 v[206:209], v[174:177], v[4:7], v[206:209]
	global_load_dwordx4 v[162:165], v220, s[24:25] offset:384
	global_load_dwordx4 v[166:169], v220, s[26:27] offset:384
	global_load_dwordx4 v[170:173], v220, s[28:29] offset:384
	global_load_dwordx4 v[174:177], v220, s[30:31] offset:384
	s_waitcnt vmcnt(52)
	v_fmamk_f32 v235, v40, 0x3fb8aa3b, v194
	v_mov_b32_e32 v40, 0xff800000
	v_cndmask_b32_e64 v40, v40, v235, s[40:41]
	v_fmamk_f32 v235, v41, 0x3fb8aa3b, v195
	v_mov_b32_e32 v41, 0xff800000
	v_cndmask_b32_e64 v41, v41, v235, s[42:43]
	v_fmamk_f32 v235, v42, 0x3fb8aa3b, v196
	v_mov_b32_e32 v42, 0xff800000
	v_cndmask_b32_e64 v42, v42, v235, s[44:45]
	v_fmamk_f32 v235, v43, 0x3fb8aa3b, v197
	v_mov_b32_e32 v43, 0xff800000
	v_cndmask_b32_e64 v43, v43, v235, s[46:47]
	v_fmamk_f32 v235, v44, 0x3fb8aa3b, v198
	v_mov_b32_e32 v44, 0xff800000
	v_cndmask_b32_e64 v44, v44, v235, s[48:49]
	v_fmamk_f32 v235, v45, 0x3fb8aa3b, v199
	v_mov_b32_e32 v45, 0xff800000
	v_cndmask_b32_e64 v45, v45, v235, s[50:51]
	v_fmamk_f32 v235, v46, 0x3fb8aa3b, v200
	v_mov_b32_e32 v46, 0xff800000
	v_cndmask_b32_e64 v46, v46, v235, s[52:53]
	v_fmamk_f32 v235, v47, 0x3fb8aa3b, v201
	v_mov_b32_e32 v47, 0xff800000
	v_cndmask_b32_e64 v47, v47, v235, s[54:55]
	s_waitcnt vmcnt(20)
	v_mfma_f32_16x16x32_bf16 v[194:197], v[72:75], v[0:3], 0
	v_mfma_f32_16x16x32_bf16 v[198:201], v[80:83], v[0:3], 0
	v_mfma_f32_16x16x32_bf16 v[194:197], v[76:79], v[4:7], v[194:197]
	v_mfma_f32_16x16x32_bf16 v[198:201], v[84:87], v[4:7], v[198:201]
	global_load_dwordx4 v[72:75], v220, s[24:25] offset:512
	global_load_dwordx4 v[76:79], v220, s[26:27] offset:512
	global_load_dwordx4 v[80:83], v220, s[28:29] offset:512
	global_load_dwordx4 v[84:87], v220, s[30:31] offset:512
	s_waitcnt vmcnt(44)
	v_fmamk_f32 v235, v48, 0x3fb8aa3b, v202
	v_mov_b32_e32 v48, 0xff800000
	v_cndmask_b32_e64 v48, v48, v235, s[40:41]
	v_fmamk_f32 v235, v49, 0x3fb8aa3b, v203
	v_mov_b32_e32 v49, 0xff800000
	v_cndmask_b32_e64 v49, v49, v235, s[42:43]
	v_fmamk_f32 v235, v50, 0x3fb8aa3b, v204
	v_mov_b32_e32 v50, 0xff800000
	v_cndmask_b32_e64 v50, v50, v235, s[44:45]
	v_fmamk_f32 v235, v51, 0x3fb8aa3b, v205
	v_mov_b32_e32 v51, 0xff800000
	v_cndmask_b32_e64 v51, v51, v235, s[46:47]
	v_fmamk_f32 v235, v52, 0x3fb8aa3b, v206
	v_mov_b32_e32 v52, 0xff800000
	v_cndmask_b32_e64 v52, v52, v235, s[48:49]
	v_fmamk_f32 v235, v53, 0x3fb8aa3b, v207
	v_mov_b32_e32 v53, 0xff800000
	v_cndmask_b32_e64 v53, v53, v235, s[50:51]
	v_fmamk_f32 v235, v54, 0x3fb8aa3b, v208
	v_mov_b32_e32 v54, 0xff800000
	v_cndmask_b32_e64 v54, v54, v235, s[52:53]
	v_fmamk_f32 v235, v55, 0x3fb8aa3b, v209
	v_mov_b32_e32 v55, 0xff800000
	v_cndmask_b32_e64 v55, v55, v235, s[54:55]
	s_waitcnt vmcnt(20)
	v_mfma_f32_16x16x32_bf16 v[202:205], v[88:91], v[0:3], 0
	v_mfma_f32_16x16x32_bf16 v[206:209], v[96:99], v[0:3], 0
	v_mfma_f32_16x16x32_bf16 v[202:205], v[92:95], v[4:7], v[202:205]
	v_mfma_f32_16x16x32_bf16 v[206:209], v[100:103], v[4:7], v[206:209]
	global_load_dwordx4 v[88:91], v220, s[24:25] offset:640
	global_load_dwordx4 v[92:95], v220, s[26:27] offset:640
	global_load_dwordx4 v[96:99], v220, s[28:29] offset:640
	global_load_dwordx4 v[100:103], v220, s[30:31] offset:640
	s_waitcnt vmcnt(40)
	v_fmamk_f32 v235, v56, 0x3fb8aa3b, v194
	v_mov_b32_e32 v56, 0xff800000
	v_cndmask_b32_e64 v56, v56, v235, s[40:41]
	v_fmamk_f32 v235, v57, 0x3fb8aa3b, v195
	v_mov_b32_e32 v57, 0xff800000
	v_cndmask_b32_e64 v57, v57, v235, s[42:43]
	v_fmamk_f32 v235, v58, 0x3fb8aa3b, v196
	v_mov_b32_e32 v58, 0xff800000
	v_cndmask_b32_e64 v58, v58, v235, s[44:45]
	v_fmamk_f32 v235, v59, 0x3fb8aa3b, v197
	v_mov_b32_e32 v59, 0xff800000
	v_cndmask_b32_e64 v59, v59, v235, s[46:47]
	v_fmamk_f32 v235, v60, 0x3fb8aa3b, v198
	v_mov_b32_e32 v60, 0xff800000
	v_cndmask_b32_e64 v60, v60, v235, s[48:49]
	v_fmamk_f32 v235, v61, 0x3fb8aa3b, v199
	v_mov_b32_e32 v61, 0xff800000
	v_cndmask_b32_e64 v61, v61, v235, s[50:51]
	v_fmamk_f32 v235, v62, 0x3fb8aa3b, v200
	v_mov_b32_e32 v62, 0xff800000
	v_cndmask_b32_e64 v62, v62, v235, s[52:53]
	v_fmamk_f32 v235, v63, 0x3fb8aa3b, v201
	v_mov_b32_e32 v63, 0xff800000
	v_cndmask_b32_e64 v63, v63, v235, s[54:55]
	s_nop 7
	s_waitcnt vmcnt(32)
	v_fmamk_f32 v235, v64, 0x3fb8aa3b, v202
	v_mov_b32_e32 v64, 0xff800000
	v_cndmask_b32_e64 v64, v64, v235, s[40:41]
	v_fmamk_f32 v235, v65, 0x3fb8aa3b, v203
	v_mov_b32_e32 v65, 0xff800000
	v_cndmask_b32_e64 v65, v65, v235, s[42:43]
	v_fmamk_f32 v235, v66, 0x3fb8aa3b, v204
	v_mov_b32_e32 v66, 0xff800000
	v_cndmask_b32_e64 v66, v66, v235, s[44:45]
	v_fmamk_f32 v235, v67, 0x3fb8aa3b, v205
	v_mov_b32_e32 v67, 0xff800000
	v_cndmask_b32_e64 v67, v67, v235, s[46:47]
	v_fmamk_f32 v235, v68, 0x3fb8aa3b, v206
	v_mov_b32_e32 v68, 0xff800000
	v_cndmask_b32_e64 v68, v68, v235, s[48:49]
	v_fmamk_f32 v235, v69, 0x3fb8aa3b, v207
	v_mov_b32_e32 v69, 0xff800000
	v_cndmask_b32_e64 v69, v69, v235, s[50:51]
	v_fmamk_f32 v235, v70, 0x3fb8aa3b, v208
	v_mov_b32_e32 v70, 0xff800000
	v_cndmask_b32_e64 v70, v70, v235, s[52:53]
	v_fmamk_f32 v235, v71, 0x3fb8aa3b, v209
	v_mov_b32_e32 v71, 0xff800000
	v_cndmask_b32_e64 v71, v71, v235, s[54:55]
	v_max3_f32 v233, v8, v9, v10
	v_max_f32_e32 v233, v233, v11
	v_max_f32_e32 v233, v233, v12
	v_max_f32_e32 v233, v233, v13
	v_max_f32_e32 v233, v233, v14
	v_max_f32_e32 v233, v233, v15
	v_max_f32_e32 v233, v233, v16
	v_max_f32_e32 v233, v233, v17
	v_max_f32_e32 v233, v233, v18
	v_max_f32_e32 v233, v233, v19
	v_max_f32_e32 v233, v233, v20
	v_max_f32_e32 v233, v233, v21
	v_max_f32_e32 v233, v233, v22
	v_max_f32_e32 v233, v233, v23
	v_max_f32_e32 v233, v233, v24
	v_max_f32_e32 v233, v233, v25
	v_max_f32_e32 v233, v233, v26
	v_max_f32_e32 v233, v233, v27
	v_max_f32_e32 v233, v233, v28
	v_max_f32_e32 v233, v233, v29
	v_max_f32_e32 v233, v233, v30
	v_max_f32_e32 v233, v233, v31
	v_max_f32_e32 v233, v233, v32
	v_max_f32_e32 v233, v233, v33
	v_max_f32_e32 v233, v233, v34
	v_max_f32_e32 v233, v233, v35
	v_max_f32_e32 v233, v233, v36
	v_max_f32_e32 v233, v233, v37
	v_max_f32_e32 v233, v233, v38
	v_max_f32_e32 v233, v233, v39
	v_max_f32_e32 v233, v233, v40
	v_max_f32_e32 v233, v233, v41
	v_max_f32_e32 v233, v233, v42
	v_max_f32_e32 v233, v233, v43
	v_max_f32_e32 v233, v233, v44
	v_max_f32_e32 v233, v233, v45
	v_max_f32_e32 v233, v233, v46
	v_max_f32_e32 v233, v233, v47
	v_max_f32_e32 v233, v233, v48
	v_max_f32_e32 v233, v233, v49
	v_max_f32_e32 v233, v233, v50
	v_max_f32_e32 v233, v233, v51
	v_max_f32_e32 v233, v233, v52
	v_max_f32_e32 v233, v233, v53
	v_max_f32_e32 v233, v233, v54
	v_max_f32_e32 v233, v233, v55
	v_max_f32_e32 v233, v233, v56
	v_max_f32_e32 v233, v233, v57
	v_max_f32_e32 v233, v233, v58
	v_max_f32_e32 v233, v233, v59
	v_max_f32_e32 v233, v233, v60
	v_max_f32_e32 v233, v233, v61
	v_max_f32_e32 v233, v233, v62
	v_max_f32_e32 v233, v233, v63
	v_max_f32_e32 v233, v233, v64
	v_max_f32_e32 v233, v233, v65
	v_max_f32_e32 v233, v233, v66
	v_max_f32_e32 v233, v233, v67
	v_max_f32_e32 v233, v233, v68
	v_max_f32_e32 v233, v233, v69
	v_max_f32_e32 v233, v233, v70
	v_max_f32_e32 v233, v233, v71
	ds_bpermute_b32 v235, v223, v233
	s_waitcnt lgkmcnt(0)
	v_max_f32_e32 v233, v233, v235
	ds_bpermute_b32 v235, v232, v233
	s_waitcnt lgkmcnt(0)
	v_max_f32_e32 v233, v233, v235
	v_mov_b32_e32 v234, 0
	v_sub_f32_e32 v8, v8, v233
	v_exp_f32_e32 v8, v8
	v_sub_f32_e32 v9, v9, v233
	v_add_f32_e32 v234, v234, v8
	v_exp_f32_e32 v9, v9
	v_sub_f32_e32 v10, v10, v233
	v_add_f32_e32 v234, v234, v9
	v_exp_f32_e32 v10, v10
	v_sub_f32_e32 v11, v11, v233
	v_add_f32_e32 v234, v234, v10
	v_exp_f32_e32 v11, v11
	v_sub_f32_e32 v12, v12, v233
	v_add_f32_e32 v234, v234, v11
	v_exp_f32_e32 v12, v12
	v_sub_f32_e32 v13, v13, v233
	v_add_f32_e32 v234, v234, v12
	v_exp_f32_e32 v13, v13
	v_sub_f32_e32 v14, v14, v233
	v_add_f32_e32 v234, v234, v13
	v_exp_f32_e32 v14, v14
	v_sub_f32_e32 v15, v15, v233
	v_add_f32_e32 v234, v234, v14
	v_exp_f32_e32 v15, v15
	v_sub_f32_e32 v16, v16, v233
	v_add_f32_e32 v234, v234, v15
	v_exp_f32_e32 v16, v16
	v_sub_f32_e32 v17, v17, v233
	v_add_f32_e32 v234, v234, v16
	v_exp_f32_e32 v17, v17
	v_sub_f32_e32 v18, v18, v233
	v_add_f32_e32 v234, v234, v17
	v_exp_f32_e32 v18, v18
	v_sub_f32_e32 v19, v19, v233
	v_add_f32_e32 v234, v234, v18
	v_exp_f32_e32 v19, v19
	v_sub_f32_e32 v20, v20, v233
	v_add_f32_e32 v234, v234, v19
	v_exp_f32_e32 v20, v20
	v_sub_f32_e32 v21, v21, v233
	v_add_f32_e32 v234, v234, v20
	v_exp_f32_e32 v21, v21
	v_sub_f32_e32 v22, v22, v233
	v_add_f32_e32 v234, v234, v21
	v_exp_f32_e32 v22, v22
	v_sub_f32_e32 v23, v23, v233
	v_add_f32_e32 v234, v234, v22
	v_exp_f32_e32 v23, v23
	v_sub_f32_e32 v24, v24, v233
	v_add_f32_e32 v234, v234, v23
	v_exp_f32_e32 v24, v24
	v_sub_f32_e32 v25, v25, v233
	v_add_f32_e32 v234, v234, v24
	v_exp_f32_e32 v25, v25
	v_sub_f32_e32 v26, v26, v233
	v_add_f32_e32 v234, v234, v25
	v_exp_f32_e32 v26, v26
	v_sub_f32_e32 v27, v27, v233
	v_add_f32_e32 v234, v234, v26
	v_exp_f32_e32 v27, v27
	v_sub_f32_e32 v28, v28, v233
	v_add_f32_e32 v234, v234, v27
	v_exp_f32_e32 v28, v28
	v_sub_f32_e32 v29, v29, v233
	v_add_f32_e32 v234, v234, v28
	v_exp_f32_e32 v29, v29
	v_sub_f32_e32 v30, v30, v233
	v_add_f32_e32 v234, v234, v29
	v_exp_f32_e32 v30, v30
	v_sub_f32_e32 v31, v31, v233
	v_add_f32_e32 v234, v234, v30
	v_exp_f32_e32 v31, v31
	v_sub_f32_e32 v32, v32, v233
	v_add_f32_e32 v234, v234, v31
	v_exp_f32_e32 v32, v32
	v_sub_f32_e32 v33, v33, v233
	v_add_f32_e32 v234, v234, v32
	v_exp_f32_e32 v33, v33
	v_sub_f32_e32 v34, v34, v233
	v_add_f32_e32 v234, v234, v33
	v_exp_f32_e32 v34, v34
	v_sub_f32_e32 v35, v35, v233
	v_add_f32_e32 v234, v234, v34
	v_exp_f32_e32 v35, v35
	v_sub_f32_e32 v36, v36, v233
	v_add_f32_e32 v234, v234, v35
	v_exp_f32_e32 v36, v36
	v_sub_f32_e32 v37, v37, v233
	v_add_f32_e32 v234, v234, v36
	v_exp_f32_e32 v37, v37
	v_sub_f32_e32 v38, v38, v233
	v_add_f32_e32 v234, v234, v37
	v_exp_f32_e32 v38, v38
	v_sub_f32_e32 v39, v39, v233
	v_add_f32_e32 v234, v234, v38
	v_exp_f32_e32 v39, v39
	v_sub_f32_e32 v40, v40, v233
	v_add_f32_e32 v234, v234, v39
	v_exp_f32_e32 v40, v40
	v_sub_f32_e32 v41, v41, v233
	v_add_f32_e32 v234, v234, v40
	v_exp_f32_e32 v41, v41
	v_sub_f32_e32 v42, v42, v233
	v_add_f32_e32 v234, v234, v41
	v_exp_f32_e32 v42, v42
	v_sub_f32_e32 v43, v43, v233
	v_add_f32_e32 v234, v234, v42
	v_exp_f32_e32 v43, v43
	v_sub_f32_e32 v44, v44, v233
	v_add_f32_e32 v234, v234, v43
	v_exp_f32_e32 v44, v44
	v_sub_f32_e32 v45, v45, v233
	v_add_f32_e32 v234, v234, v44
	v_exp_f32_e32 v45, v45
	v_sub_f32_e32 v46, v46, v233
	v_add_f32_e32 v234, v234, v45
	v_exp_f32_e32 v46, v46
	v_sub_f32_e32 v47, v47, v233
	v_add_f32_e32 v234, v234, v46
	v_exp_f32_e32 v47, v47
	v_sub_f32_e32 v48, v48, v233
	v_add_f32_e32 v234, v234, v47
	v_exp_f32_e32 v48, v48
	v_sub_f32_e32 v49, v49, v233
	v_add_f32_e32 v234, v234, v48
	v_exp_f32_e32 v49, v49
	v_sub_f32_e32 v50, v50, v233
	v_add_f32_e32 v234, v234, v49
	v_exp_f32_e32 v50, v50
	v_sub_f32_e32 v51, v51, v233
	v_add_f32_e32 v234, v234, v50
	v_exp_f32_e32 v51, v51
	v_sub_f32_e32 v52, v52, v233
	v_add_f32_e32 v234, v234, v51
	v_exp_f32_e32 v52, v52
	v_sub_f32_e32 v53, v53, v233
	v_add_f32_e32 v234, v234, v52
	v_exp_f32_e32 v53, v53
	v_sub_f32_e32 v54, v54, v233
	v_add_f32_e32 v234, v234, v53
	v_exp_f32_e32 v54, v54
	v_sub_f32_e32 v55, v55, v233
	v_add_f32_e32 v234, v234, v54
	v_exp_f32_e32 v55, v55
	v_sub_f32_e32 v56, v56, v233
	v_add_f32_e32 v234, v234, v55
	v_exp_f32_e32 v56, v56
	v_sub_f32_e32 v57, v57, v233
	v_add_f32_e32 v234, v234, v56
	v_exp_f32_e32 v57, v57
	v_sub_f32_e32 v58, v58, v233
	v_add_f32_e32 v234, v234, v57
	v_exp_f32_e32 v58, v58
	v_sub_f32_e32 v59, v59, v233
	v_add_f32_e32 v234, v234, v58
	v_exp_f32_e32 v59, v59
	v_sub_f32_e32 v60, v60, v233
	v_add_f32_e32 v234, v234, v59
	v_exp_f32_e32 v60, v60
	v_sub_f32_e32 v61, v61, v233
	v_add_f32_e32 v234, v234, v60
	v_exp_f32_e32 v61, v61
	v_sub_f32_e32 v62, v62, v233
	v_add_f32_e32 v234, v234, v61
	v_exp_f32_e32 v62, v62
	v_sub_f32_e32 v63, v63, v233
	v_add_f32_e32 v234, v234, v62
	v_exp_f32_e32 v63, v63
	v_sub_f32_e32 v64, v64, v233
	v_add_f32_e32 v234, v234, v63
	v_exp_f32_e32 v64, v64
	v_sub_f32_e32 v65, v65, v233
	v_add_f32_e32 v234, v234, v64
	v_exp_f32_e32 v65, v65
	v_sub_f32_e32 v66, v66, v233
	v_add_f32_e32 v234, v234, v65
	v_exp_f32_e32 v66, v66
	v_sub_f32_e32 v67, v67, v233
	v_add_f32_e32 v234, v234, v66
	v_exp_f32_e32 v67, v67
	v_sub_f32_e32 v68, v68, v233
	v_add_f32_e32 v234, v234, v67
	v_exp_f32_e32 v68, v68
	v_sub_f32_e32 v69, v69, v233
	v_add_f32_e32 v234, v234, v68
	v_exp_f32_e32 v69, v69
	v_sub_f32_e32 v70, v70, v233
	v_add_f32_e32 v234, v234, v69
	v_exp_f32_e32 v70, v70
	v_sub_f32_e32 v71, v71, v233
	v_add_f32_e32 v234, v234, v70
	v_exp_f32_e32 v71, v71
	s_nop 0
	v_add_f32_e32 v234, v234, v71
	ds_bpermute_b32 v235, v223, v234
	v_cvt_pk_bf16_f32 v8, v8, v9
	v_cvt_pk_bf16_f32 v9, v10, v11
	v_cvt_pk_bf16_f32 v10, v12, v13
	v_cvt_pk_bf16_f32 v11, v14, v15
	v_cvt_pk_bf16_f32 v16, v16, v17
	v_cvt_pk_bf16_f32 v17, v18, v19
	v_cvt_pk_bf16_f32 v18, v20, v21
	v_cvt_pk_bf16_f32 v19, v22, v23
	v_cvt_pk_bf16_f32 v24, v24, v25
	v_cvt_pk_bf16_f32 v25, v26, v27
	v_cvt_pk_bf16_f32 v26, v28, v29
	v_cvt_pk_bf16_f32 v27, v30, v31
	v_cvt_pk_bf16_f32 v32, v32, v33
	v_cvt_pk_bf16_f32 v33, v34, v35
	v_cvt_pk_bf16_f32 v34, v36, v37
	v_cvt_pk_bf16_f32 v35, v38, v39
	v_cvt_pk_bf16_f32 v40, v40, v41
	v_cvt_pk_bf16_f32 v41, v42, v43
	v_cvt_pk_bf16_f32 v42, v44, v45
	v_cvt_pk_bf16_f32 v43, v46, v47
	v_cvt_pk_bf16_f32 v48, v48, v49
	v_cvt_pk_bf16_f32 v49, v50, v51
	v_cvt_pk_bf16_f32 v50, v52, v53
	v_cvt_pk_bf16_f32 v51, v54, v55
	v_cvt_pk_bf16_f32 v56, v56, v57
	v_cvt_pk_bf16_f32 v57, v58, v59
	v_cvt_pk_bf16_f32 v58, v60, v61
	v_cvt_pk_bf16_f32 v59, v62, v63
	v_cvt_pk_bf16_f32 v64, v64, v65
	v_cvt_pk_bf16_f32 v65, v66, v67
	v_cvt_pk_bf16_f32 v66, v68, v69
	v_cvt_pk_bf16_f32 v67, v70, v71
	global_load_dwordx4 v[12:15], v220, s[24:25] offset:768
	global_load_dwordx4 v[20:23], v220, s[26:27] offset:768
	global_load_dwordx4 v[28:31], v220, s[28:29] offset:768
	global_load_dwordx4 v[36:39], v220, s[30:31] offset:768
	global_load_dwordx4 v[44:47], v220, s[24:25] offset:896
	global_load_dwordx4 v[52:55], v220, s[26:27] offset:896
	global_load_dwordx4 v[60:63], v220, s[28:29] offset:896
	global_load_dwordx4 v[68:71], v220, s[30:31] offset:896
	s_waitcnt lgkmcnt(0)
	v_add_f32_e32 v234, v234, v235
	ds_bpermute_b32 v235, v232, v234
	s_waitcnt lgkmcnt(0)
	v_add_f32_e32 v234, v234, v235
	s_waitcnt vmcnt(28)
	v_mfma_f32_16x16x32_bf16 v[178:181], v[104:107], v[8:11], v[178:181]
	v_mfma_f32_16x16x32_bf16 v[182:185], v[108:111], v[8:11], v[182:185]
	v_mfma_f32_16x16x32_bf16 v[186:189], v[112:115], v[8:11], v[186:189]
	v_mfma_f32_16x16x32_bf16 v[190:193], v[116:119], v[8:11], v[190:193]
	s_waitcnt vmcnt(24)
	v_mfma_f32_16x16x32_bf16 v[178:181], v[120:123], v[16:19], v[178:181]
	v_mfma_f32_16x16x32_bf16 v[182:185], v[124:127], v[16:19], v[182:185]
	v_mfma_f32_16x16x32_bf16 v[186:189], v[128:131], v[16:19], v[186:189]
	v_mfma_f32_16x16x32_bf16 v[190:193], v[132:135], v[16:19], v[190:193]
	s_waitcnt vmcnt(20)
	v_mfma_f32_16x16x32_bf16 v[178:181], v[146:149], v[24:27], v[178:181]
	v_mfma_f32_16x16x32_bf16 v[182:185], v[150:153], v[24:27], v[182:185]
	v_mfma_f32_16x16x32_bf16 v[186:189], v[154:157], v[24:27], v[186:189]
	v_mfma_f32_16x16x32_bf16 v[190:193], v[158:161], v[24:27], v[190:193]
	s_waitcnt vmcnt(16)
	v_mfma_f32_16x16x32_bf16 v[178:181], v[162:165], v[32:35], v[178:181]
	v_mfma_f32_16x16x32_bf16 v[182:185], v[166:169], v[32:35], v[182:185]
	v_mfma_f32_16x16x32_bf16 v[186:189], v[170:173], v[32:35], v[186:189]
	v_mfma_f32_16x16x32_bf16 v[190:193], v[174:177], v[32:35], v[190:193]
	s_waitcnt vmcnt(12)
	v_mfma_f32_16x16x32_bf16 v[178:181], v[72:75], v[40:43], v[178:181]
	v_mfma_f32_16x16x32_bf16 v[182:185], v[76:79], v[40:43], v[182:185]
	v_mfma_f32_16x16x32_bf16 v[186:189], v[80:83], v[40:43], v[186:189]
	v_mfma_f32_16x16x32_bf16 v[190:193], v[84:87], v[40:43], v[190:193]
	s_waitcnt vmcnt(8)
	v_mfma_f32_16x16x32_bf16 v[178:181], v[88:91], v[48:51], v[178:181]
	v_mfma_f32_16x16x32_bf16 v[182:185], v[92:95], v[48:51], v[182:185]
	v_mfma_f32_16x16x32_bf16 v[186:189], v[96:99], v[48:51], v[186:189]
	v_mfma_f32_16x16x32_bf16 v[190:193], v[100:103], v[48:51], v[190:193]
	s_waitcnt vmcnt(4)
	v_mfma_f32_16x16x32_bf16 v[178:181], v[12:15], v[56:59], v[178:181]
	v_mfma_f32_16x16x32_bf16 v[182:185], v[20:23], v[56:59], v[182:185]
	v_mfma_f32_16x16x32_bf16 v[186:189], v[28:31], v[56:59], v[186:189]
	v_mfma_f32_16x16x32_bf16 v[190:193], v[36:39], v[56:59], v[190:193]
	s_waitcnt vmcnt(0)
	v_mfma_f32_16x16x32_bf16 v[178:181], v[44:47], v[64:67], v[178:181]
	v_mfma_f32_16x16x32_bf16 v[182:185], v[52:55], v[64:67], v[182:185]
	v_mfma_f32_16x16x32_bf16 v[186:189], v[60:63], v[64:67], v[186:189]
	v_mfma_f32_16x16x32_bf16 v[190:193], v[68:71], v[64:67], v[190:193]
	v_div_scale_f32 v235, s[36:37], v234, v234, 1.0
	v_rcp_f32_e32 v236, v235
	s_nop 0
	v_fma_f32 v237, -v235, v236, 1.0
	v_fmac_f32_e32 v236, v237, v236
	v_div_scale_f32 v237, vcc, 1.0, v234, 1.0
	v_mul_f32_e32 v240, v237, v236
	v_fma_f32 v241, -v235, v240, v237
	v_fmac_f32_e32 v240, v241, v236
	v_fma_f32 v235, -v235, v240, v237
	v_div_fmas_f32 v235, v235, v236, v240
	v_div_fixup_f32 v233, v235, v234, 1.0
	s_nop 3
	v_mul_f32_e32 v178, v178, v233
	v_mul_f32_e32 v179, v179, v233
	v_mul_f32_e32 v180, v180, v233
	v_mul_f32_e32 v181, v181, v233
	v_cvt_pk_bf16_f32 v178, v178, v179
	v_cvt_pk_bf16_f32 v179, v180, v181
	global_store_dwordx2 v222, v[178:179], s[32:33]
	v_mul_f32_e32 v182, v182, v233
	v_mul_f32_e32 v183, v183, v233
	v_mul_f32_e32 v184, v184, v233
	v_mul_f32_e32 v185, v185, v233
	v_cvt_pk_bf16_f32 v182, v182, v183
	v_cvt_pk_bf16_f32 v183, v184, v185
	global_store_dwordx2 v222, v[182:183], s[32:33] offset:32
	v_mul_f32_e32 v186, v186, v233
	v_mul_f32_e32 v187, v187, v233
	v_mul_f32_e32 v188, v188, v233
	v_mul_f32_e32 v189, v189, v233
	v_cvt_pk_bf16_f32 v186, v186, v187
	v_cvt_pk_bf16_f32 v187, v188, v189
	global_store_dwordx2 v222, v[186:187], s[32:33] offset:64
	v_mul_f32_e32 v190, v190, v233
	v_mul_f32_e32 v191, v191, v233
	v_mul_f32_e32 v192, v192, v233
	v_mul_f32_e32 v193, v193, v233
	v_cvt_pk_bf16_f32 v190, v190, v191
	v_cvt_pk_bf16_f32 v191, v192, v193
	global_store_dwordx2 v222, v[190:191], s[32:33] offset:96
	s_add_u32 s7, s7, 0x200
	s_add_u32 s14, s14, 1
	s_cmp_lt_u32 s14, 4
	s_cbranch_scc1 .Lna_tile
	v_readlane_b32 s0, v245, 0
	v_readlane_b32 s1, v245, 1
	v_readlane_b32 s2, v245, 2
	v_readlane_b32 s3, v245, 3
	v_readlane_b32 s4, v245, 4
	v_readlane_b32 s5, v245, 5
	v_readlane_b32 s6, v245, 6
	v_readlane_b32 s7, v245, 7
	v_readlane_b32 s8, v245, 8
	v_readlane_b32 s9, v245, 9
	v_readlane_b32 s10, v245, 10
	v_readlane_b32 s11, v245, 11
	v_readlane_b32 s12, v245, 12
	v_readlane_b32 s13, v245, 13
	v_readlane_b32 s14, v245, 14
	v_readlane_b32 s15, v245, 15
	v_readlane_b32 s16, v245, 16
	v_readlane_b32 s17, v245, 17
	v_readlane_b32 s18, v245, 18
	v_readlane_b32 s19, v245, 19
	v_readlane_b32 s20, v245, 20
	v_readlane_b32 s21, v245, 21
	v_readlane_b32 s22, v245, 22
	v_readlane_b32 s23, v245, 23
	v_readlane_b32 s24, v245, 24
	v_readlane_b32 s25, v245, 25
	v_readlane_b32 s26, v245, 26
	v_readlane_b32 s27, v245, 27
	v_readlane_b32 s28, v245, 28
	v_readlane_b32 s29, v245, 29
	v_readlane_b32 s30, v245, 30
	v_readlane_b32 s31, v245, 31
	v_readlane_b32 s32, v245, 32
	v_readlane_b32 s33, v245, 33
	v_readlane_b32 s34, v245, 34
	v_readlane_b32 s35, v245, 35
	v_readlane_b32 s36, v245, 36
	v_readlane_b32 s37, v245, 37
	v_readlane_b32 s38, v245, 38
	v_readlane_b32 s39, v245, 39
	v_readlane_b32 s40, v245, 40
	v_readlane_b32 s41, v245, 41
	v_readlane_b32 s42, v245, 42
	v_readlane_b32 s43, v245, 43
	v_readlane_b32 s44, v245, 44
	v_readlane_b32 s45, v245, 45
	v_readlane_b32 s46, v245, 46
	v_readlane_b32 s47, v245, 47
	v_readlane_b32 s48, v245, 48
	v_readlane_b32 s49, v245, 49
	v_readlane_b32 s50, v245, 50
	v_readlane_b32 s51, v245, 51
	v_readlane_b32 s52, v245, 52
	v_readlane_b32 s53, v245, 53
	v_readlane_b32 s54, v245, 54
	v_readlane_b32 s55, v245, 55
	v_readlane_b32 s56, v245, 56
	v_readlane_b32 s57, v245, 57
	v_readlane_b32 s58, v245, 58
	v_readlane_b32 s59, v245, 59
	v_readlane_b32 s60, v245, 60
	v_readlane_b32 s61, v245, 61
	v_readlane_b32 s62, v245, 62
	v_readlane_b32 s63, v245, 63
	v_readlane_b32 s64, v244, 0
	v_readlane_b32 s65, v244, 1
	v_readlane_b32 s66, v244, 2
	v_readlane_b32 s67, v244, 3
	v_readlane_b32 s68, v244, 4
	v_readlane_b32 s69, v244, 5
	v_readlane_b32 s70, v244, 6
	v_readlane_b32 s71, v244, 7
	v_readlane_b32 s72, v244, 8
	v_readlane_b32 s73, v244, 9
	v_readlane_b32 s74, v244, 10
	v_readlane_b32 s75, v244, 11
	v_readlane_b32 s76, v244, 12
	v_readlane_b32 s77, v244, 13
	v_readlane_b32 s78, v244, 14
	v_readlane_b32 s79, v244, 15
.LBB0_1074:
	s_cmpk_gt_i32 s34, 0x3ff
	s_cbranch_scc1 .LBB0_1107
	v_readlane_b32 s0, v253, 35
	s_add_i32 s10, s35, s0
	s_lshl_b32 s0, s35, 4
	v_readlane_b32 s1, v253, 45
	s_add_i32 s11, s1, s0
	s_branch .LBB0_1094
.LBB0_1093:
	v_readlane_b32 s0, v254, 9
	s_add_i32 s34, s34, s70
	s_sub_i32 s10, s10, s70
	s_add_i32 s11, s11, s0
	s_cmpk_gt_i32 s34, 0x3ff
	v_readlane_b32 s1, v254, 10
	s_cbranch_scc1 .LBB0_1107
